# layer 1's own w_out tiles are converted in layer 1's P1 idle slot (WGs 192..255, split arrive/wait at that seam); layer 0's P4->P6 seam carries no filler items
# baseline (speedup 1.0000x reference)
; #define PG8_LAS __attribute__((address_space(3)))
;     __host__ __device__ void init(int M, int N, int G_, int c_, int skip0_, int nskip_) { S.init(M, N - nskip_ * BM, G_, c_); skip0 = skip0_; nskip = nskip_; }
; __global__ void __launch_bounds__(512, 2) mk_fwd(Args args) {
;     ...
;             { pg8::Gemm g{XB, WinT + (size_t)l * NH * DM, MT, NH, DM}; pg8::SkipOrder S; S.init(MT, NH, G, wg, C_CV / 256, 2); pg8::EpiH E{H, NH, 1};
;               pg8::gemm_phase<pg8::EpiH, pg8::SkipOrder, true, true>((PG8_LAS unsigned char*)lds, g, S, E); }
;             { pg8::Gemm g{WinT + (size_t)l * NH * DM + (size_t)C_CV * DM, XB, GW, MT, DM}; pg8::StaticOrder S; S.init(GW, MT, G, (G == 256) ? (wg + 128) % 256 : wg); pg8::EpiH E{VT, MT, 0};
;               pg8::gemm_phase<pg8::EpiH, pg8::StaticOrder, true, true>((PG8_LAS unsigned char*)lds, g, S, E); }
;             { pg8::Gemm g{PB + (size_t)l * MT * PLE, WpeT + (size_t)l * DM * PLE, MT, DM, PLE}; pg8::StaticOrder S; if (G == 256) S.init(MT, DM, 64, wg >= 192 ? wg - 192 : (1 << 20)); else S.init(MT, DM, G, wg); pg8::EpiH E{PE, DM, 0};
.LBB0_248:
	s_cmpk_lt_i32 s96, 0x380
	s_cselect_b64 s[2:3], -1, 0
	v_writelane_b32 v253, s2, 35
	s_ashr_i32 s97, s96, 31
	s_lshr_b32 s1, s97, 29
	v_writelane_b32 v253, s3, 36
	s_add_i32 s3, s96, 0x80
	s_ashr_i32 s4, s3, 31
	s_lshr_b32 s4, s4, 24
	s_add_i32 s2, s96, s1
	s_add_i32 s4, s3, s4
	s_ashr_i32 s1, s2, 3
	s_and_b32 s2, s2, -8
	s_and_b32 s4, s4, 0xffffff00
	s_mul_i32 s0, s87, s86
	s_sub_i32 s2, s96, s2
	s_ashr_i32 s87, s86, 31
	s_sub_i32 s3, s3, s4
	s_add_i32 s4, s96, 0xffffff40
	s_cmpk_gt_i32 s96, 0xbf
	s_cselect_b32 s4, s4, 0x100000
	s_cmpk_eq_i32 s86, 0x100
	s_cselect_b32 s5, s3, s96
	s_cselect_b32 s9, 64, s86
	s_cselect_b32 s8, s4, s96
	s_cmp_lt_i32 s5, 64
	s_cselect_b64 s[6:7], -1, 0
	v_writelane_b32 v253, s6, 37
	s_ashr_i32 s3, s5, 31
	s_mul_i32 s0, s0, s33
	v_writelane_b32 v253, s7, 38
	v_writelane_b32 v253, s3, 39
	s_lshr_b32 s3, s3, 29
	s_add_i32 s3, s5, s3
	s_ashr_i32 s4, s3, 3
	s_and_b32 s3, s3, -8
	s_sub_i32 s3, s5, s3
	v_writelane_b32 v253, s5, 40
	s_lshl_b32 s5, s3, 3
	s_cmpk_lt_i32 s8, 0x100
	s_cselect_b64 s[6:7], -1, 0
	v_writelane_b32 v253, s6, 41
	s_mov_b32 s29, 0
	v_mov_b32_e32 v169, 0
	v_writelane_b32 v253, s7, 42
	s_ashr_i32 s6, s8, 31
	v_writelane_b32 v253, s6, 43
	s_lshr_b32 s6, s6, 29
	s_add_i32 s6, s8, s6
	s_ashr_i32 s7, s6, 3
	s_and_b32 s6, s6, -8
	v_writelane_b32 v253, s8, 44
	s_sub_i32 s6, s8, s6
	s_lshl_b32 s8, s6, 5
	v_writelane_b32 v253, s9, 45
	s_ashr_i32 s9, s9, 31
	s_add_u32 s10, s20, 0x200
	v_writelane_b32 v253, s9, 46
	s_addc_u32 s11, s21, 0
	v_writelane_b32 v253, s10, 47
	v_mov_b32_e32 v214, 1
	v_mov_b32_e32 v215, 0x358637bd
	v_writelane_b32 v253, s11, 48
	s_add_u32 s10, s20, 0x1000
	s_addc_u32 s11, s21, 0
	v_writelane_b32 v253, s10, 49
	v_mov_b32_e32 v216, 0xbdd2d3e7
	v_mov_b64_e32 v[170:171], 0x100
	v_writelane_b32 v253, s11, 50
	s_add_u32 s10, s20, 0x1100
	s_addc_u32 s11, s21, 0
	v_writelane_b32 v253, s10, 51
	v_mov_b64_e32 v[172:173], 0xff
	v_mov_b32_e32 v217, 0x3c00
	v_writelane_b32 v253, s11, 52
	s_add_u32 s10, s20, 0x1200
	s_addc_u32 s11, s21, 0
	v_writelane_b32 v253, s10, 53
	v_mov_b32_e32 v218, 0x42a00000
	v_mov_b32_e32 v219, 0x7f800000
	v_writelane_b32 v253, s11, 54
	s_add_u32 s10, s20, 0x1300
	s_addc_u32 s11, s21, 0
	v_writelane_b32 v253, s10, 55
	s_cmp_eq_u32 s36, 15
	v_mov_b32_e32 v220, 0x2800
	v_writelane_b32 v253, s11, 56
	s_cselect_b64 s[10:11], -1, 0
	v_writelane_b32 v253, s10, 57
	s_cmp_eq_u32 s36, 14
	v_mov_b32_e32 v221, 0xff800000
	v_writelane_b32 v253, s11, 58
	s_cselect_b64 s[10:11], -1, 0
	v_writelane_b32 v253, s10, 59
	s_cmp_eq_u32 s36, 13
	v_mov_b32_e32 v222, 0xf0000
	v_writelane_b32 v253, s11, 60
	s_cselect_b64 s[10:11], -1, 0
	v_writelane_b32 v253, s10, 61
	s_cmp_eq_u32 s36, 12
	s_movk_i32 s69, 0x2000
	v_writelane_b32 v253, s11, 62
	s_cselect_b64 s[10:11], -1, 0
	v_writelane_b32 v253, s10, 63
	s_cmp_eq_u32 s36, 11
	s_mov_b32 s88, 0x10000
	v_writelane_b32 v254, s11, 0
	s_cselect_b64 s[10:11], -1, 0
	v_writelane_b32 v254, s10, 1
	s_cmp_eq_u32 s36, 10
	s_movk_i32 s89, 0x4000
	v_writelane_b32 v254, s11, 2
	s_cselect_b64 s[10:11], -1, 0
	v_writelane_b32 v254, s10, 3
	s_cmp_eq_u32 s36, 9
	s_movk_i32 s84, 0x6000
	v_writelane_b32 v254, s11, 4
	s_cselect_b64 s[10:11], -1, 0
	v_writelane_b32 v254, s10, 5
	s_cmp_eq_u32 s36, 8
	s_mov_b32 s85, 0x18000
	v_writelane_b32 v254, s11, 6
	s_cselect_b64 s[10:11], -1, 0
	v_writelane_b32 v254, s10, 7
	s_cmp_eq_u32 s36, 7
	s_mov_b32 s90, 0x8000
	v_writelane_b32 v254, s11, 8
	s_cselect_b64 s[10:11], -1, 0
	v_writelane_b32 v254, s10, 9
	s_cmp_eq_u32 s36, 6
	s_mov_b32 s70, 0xa000
	v_writelane_b32 v254, s11, 10
	s_cselect_b64 s[10:11], -1, 0
	v_writelane_b32 v254, s10, 11
	s_cmp_eq_u32 s36, 5
	s_mov_b32 s91, 0xc000
	v_writelane_b32 v254, s11, 12
	s_cselect_b64 s[10:11], -1, 0
	v_writelane_b32 v254, s10, 13
	s_cmp_eq_u32 s36, 4
	s_mov_b32 s71, 0xe000
	v_writelane_b32 v254, s11, 14
	s_cselect_b64 s[10:11], -1, 0
	v_writelane_b32 v254, s10, 15
	s_cmp_eq_u32 s36, 3
	s_movk_i32 s92, 0x1000
	v_writelane_b32 v254, s11, 16
	s_cselect_b64 s[10:11], -1, 0
	v_writelane_b32 v254, s10, 17
	s_cmp_eq_u32 s36, 2
	s_mov_b32 s72, 0x42a00000
	v_writelane_b32 v254, s11, 18
	s_cselect_b64 s[10:11], -1, 0
	v_writelane_b32 v254, s10, 19
	s_cmp_eq_u32 s36, 1
	s_mov_b32 s33, 0xff800000
	v_writelane_b32 v254, s11, 20
	s_cselect_b64 s[10:11], -1, 0
	v_writelane_b32 v254, s10, 21
	s_cmp_eq_u32 s36, 0
	s_mov_b32 s93, 0x800000
	v_writelane_b32 v254, s11, 22
	s_cselect_b64 s[10:11], -1, 0
	s_lshl_b32 s9, s36, 8
	v_writelane_b32 v254, s10, 23
	s_add_u32 s9, s20, s9
	v_readlane_b32 s36, v253, 18
	v_writelane_b32 v254, s11, 24
	s_addc_u32 s10, s21, 0
	s_add_u32 s12, s9, 0x1400
	s_addc_u32 s13, s10, 0
	v_writelane_b32 v254, s12, 25
	v_readlane_b32 s46, v253, 28
	v_readlane_b32 s47, v253, 29
	v_writelane_b32 v254, s13, 26
	s_add_u32 s12, s20, 0x3500
	s_addc_u32 s13, s21, 0
	v_writelane_b32 v254, s12, 27
	s_mov_b64 s[74:75], 0x80000
	s_mov_b64 s[30:31], 0x80
	v_writelane_b32 v254, s13, 28
	s_add_u32 s12, s20, 0x3400
	s_addc_u32 s13, s21, 0
	v_writelane_b32 v254, s12, 29
	s_mov_b64 s[34:35], 0xf0000
	v_readlane_b32 s37, v253, 19
	v_writelane_b32 v254, s13, 30
	s_add_u32 s12, s9, 0x2400
	s_addc_u32 s13, s10, 0
	v_writelane_b32 v254, s12, 31
	s_add_i32 s9, s14, 0x1c80
	s_cmp_lg_u64 s[46:47], 0
	v_writelane_b32 v254, s13, 32
	v_writelane_b32 v254, s9, 33
	s_cselect_b64 s[10:11], -1, 0
	v_writelane_b32 v254, s10, 34
	s_cmpk_lt_i32 s96, 0x100
	v_readlane_b32 s38, v253, 20
	v_writelane_b32 v254, s11, 35
	s_cselect_b64 s[10:11], -1, 0
	v_writelane_b32 v254, s10, 36
	s_lshl_b32 s9, s96, 9
	v_readlane_b32 s39, v253, 21
	v_writelane_b32 v254, s11, 37
	v_writelane_b32 v254, s9, 38
; #define PG8_LAS __attribute__((address_space(3)))
;     __host__ __device__ void init(int M, int N, int G_, int c_, int skip0_, int nskip_) { S.init(M, N - nskip_ * BM, G_, c_); skip0 = skip0_; nskip = nskip_; }
;     __host__ __device__ bool next(int i, Unit& u) const { if (!S.next(i, u)) return false; if (u.pn >= skip0) u.pn += nskip; return true; }
;     __host__ __device__ bool next(int i, Unit& u) const {
;         const long L = (long)i * G + c; if (L >= nwg) return false;
;         int wgid = (int)L; { const int q = nwg / NXCD, r = nwg % NXCD, xcd = wgid % NXCD, off = wgid / NXCD; wgid = (xcd < r ? xcd * (q + 1) : r * (q + 1) + (xcd - r) * q) + off; }
;         const int nig = WGM * nN, gid = wgid / nig, fm = gid * WGM, gsz = (nM - fm) < WGM ? (nM - fm) : WGM;
;         u.pm = fm + ((wgid % nig) % gsz); u.pn = (wgid % nig) / gsz; return true;
;     }
; __global__ void __launch_bounds__(512, 2) mk_fwd(Args args) {
;     ...
;             { pg8::Gemm g{XB, WinT + (size_t)l * NH * DM, MT, NH, DM}; pg8::SkipOrder S; S.init(MT, NH, G, wg, C_CV / 256, 2); pg8::EpiH E{H, NH, 1};
;               pg8::gemm_phase<pg8::EpiH, pg8::SkipOrder, true, true>((PG8_LAS unsigned char*)lds, g, S, E); }
;             { pg8::Gemm g{WinT + (size_t)l * NH * DM + (size_t)C_CV * DM, XB, GW, MT, DM}; pg8::StaticOrder S; S.init(GW, MT, G, (G == 256) ? (wg + 128) % 256 : wg); pg8::EpiH E{VT, MT, 0};
;               pg8::gemm_phase<pg8::EpiH, pg8::StaticOrder, true, true>((PG8_LAS unsigned char*)lds, g, S, E); }
;             { pg8::Gemm g{PB + (size_t)l * MT * PLE, WpeT + (size_t)l * DM * PLE, MT, DM, PLE}; pg8::StaticOrder S; if (G == 256) S.init(MT, DM, 64, wg >= 192 ? wg - 192 : (1 << 20)); else S.init(MT, DM, G, wg); pg8::EpiH E{PE, DM, 0};
	s_lshl_b32 s9, s86, 9
	s_cmpk_lt_i32 s96, 0x200
	v_writelane_b32 v254, s9, 39
	s_cselect_b64 s[10:11], -1, 0
	v_writelane_b32 v254, s10, 40
	s_add_i32 s9, s14, 0x2180
	v_readlane_b32 s40, v253, 22
	v_writelane_b32 v254, s11, 41
	v_writelane_b32 v254, s9, 42
	s_add_i32 s9, s14, 0x2e80
	v_writelane_b32 v254, s9, 43
	s_lshl_b32 s9, s2, 5
	s_movk_i32 s100, 0x2680
	s_cmpk_eq_i32 s86, 0x100
	s_cselect_b32 s100, 0x7000, s100
	s_add_i32 s10, s14, s100
	s_cmp_gt_i32 s23, 7
	v_writelane_b32 v254, s10, 44
	s_cselect_b64 s[10:11], -1, 0
	v_writelane_b32 v254, s10, 45
	v_readlane_b32 s41, v253, 23
	v_readlane_b32 s42, v253, 24
	v_writelane_b32 v254, s11, 46
	s_add_i32 s10, s14, 0x2a80
	v_writelane_b32 v254, s10, 47
	s_cmp_lt_i32 s2, 0
	s_movk_i32 s10, 0x71
	s_cselect_b32 s10, s10, 0x70
	s_mul_i32 s10, s2, s10
	s_mul_i32 s2, s2, 33
	s_cselect_b32 s2, s2, s9
	s_add_i32 s10, s10, s1
	s_mul_hi_i32 s9, s10, 0x92492493
	s_add_i32 s9, s9, s10
	s_lshr_b32 s11, s9, 31
	s_ashr_i32 s9, s9, 7
	s_add_i32 s9, s9, s11
	s_mul_i32 s11, s9, 0xe0
	s_sub_i32 s10, s10, s11
	s_bfe_u32 s11, s10, 0x3001c
	s_add_i32 s11, s10, s11
	s_sext_i32_i16 s12, s11
	s_and_b32 s11, s11, 0xfff8
	s_sub_i32 s11, s10, s11
	s_lshl_b32 s9, s9, 3
	s_sext_i32_i16 s11, s11
	s_add_i32 s14, s9, s11
	s_ashr_i32 s9, s12, 3
	s_add_i32 s11, s9, 2
	s_cmpk_lt_i32 s10, 0x80
	s_cselect_b32 s12, s9, s11
	s_cmp_lt_i32 s3, 0
	s_mul_i32 s3, s3, 9
	s_cselect_b32 s3, s3, s5
	s_add_i32 s3, s3, s4
	s_ashr_i32 s4, s3, 31
	s_lshr_b32 s4, s4, 24
	s_add_i32 s4, s3, s4
	s_and_b32 s5, s4, 0xffffff00
	s_sub_i32 s5, s3, s5
	s_ashr_i32 s3, s4, 8
	s_lshl_b32 s4, s3, 3
	s_sub_i32 s3, 2, s4
	s_min_u32 s9, s3, 8
	s_cmp_lt_i32 s6, 0
	s_mul_i32 s6, s6, 33
	s_cselect_b32 s3, s6, s8
	s_add_i32 s3, s3, s7
	s_ashr_i32 s6, s3, 31
	s_lshr_b32 s6, s6, 26
	s_add_i32 s6, s3, s6
	s_and_b32 s7, s6, 0xffc0
	s_sub_i32 s3, s3, s7
	s_bfe_i32 s7, s3, 0x80000
	s_bfe_u32 s7, s7, 0x3000c
	s_add_i32 s1, s2, s1
	s_add_i32 s7, s3, s7
	s_ashr_i32 s2, s1, 31
	s_and_b32 s8, s7, 0xf8
	s_lshr_b32 s2, s2, 26
	s_sub_i32 s3, s3, s8
	s_add_i32 s8, s1, s2
	s_and_b32 s2, s8, 0xffc0
	s_sub_i32 s1, s1, s2
	s_bfe_i32 s2, s1, 0x80000
	s_bfe_u32 s2, s2, 0x3000c
	s_add_i32 s10, s1, s2
	s_and_b32 s2, s10, 0xf8
	s_sub_i32 s1, s1, s2
	s_ashr_i32 s2, s6, 6
	s_bfe_i32 s6, s7, 0x80000
	s_lshl_b32 s2, s2, 3
	s_sext_i32_i16 s6, s6
	s_sext_i32_i8 s3, s3
	s_add_i32 s24, s2, s3
	s_ashr_i32 s2, s6, 3
	v_writelane_b32 v254, s2, 48
	s_lshr_b32 s2, s6, 3
	s_bfe_i64 s[2:3], s[2:3], 0x100000
	s_lshl_b64 s[2:3], s[2:3], 17
	v_writelane_b32 v254, s2, 49
	s_sext_i32_i8 s1, s1
	s_ashr_i32 s25, s24, 31
	v_writelane_b32 v254, s3, 50
	s_ashr_i32 s2, s8, 6
	s_bfe_i32 s3, s10, 0x80000
	s_lshl_b32 s2, s2, 3
	s_sext_i32_i16 s3, s3
	s_add_i32 s6, s2, s1
	s_lshr_b32 s2, s3, 3
	s_ashr_i32 s1, s3, 3
	s_bfe_i64 s[2:3], s[2:3], 0x100000
	v_writelane_b32 v254, s1, 51
	s_lshl_b64 s[2:3], s[2:3], 20
	v_writelane_b32 v254, s2, 52
	s_ashr_i32 s15, s14, 31
	v_cvt_f32_ubyte0_e32 v1, s9
	v_writelane_b32 v254, s3, 53
	s_mov_b32 s2, s24
	v_writelane_b32 v254, s2, 54
	s_ashr_i32 s13, s12, 31
	v_cvt_f32_i32_e32 v0, s5
	v_writelane_b32 v254, s3, 55
	s_lshl_b64 s[2:3], s[24:25], 17
	v_writelane_b32 v254, s2, 56
	v_rcp_iflag_f32_e32 v2, v1
	s_ashr_i32 s7, s6, 31
	v_writelane_b32 v254, s3, 57
	s_mov_b32 s2, s14
	v_writelane_b32 v254, s2, 58
	v_mul_f32_e32 v2, v0, v2
	v_trunc_f32_e32 v2, v2
	v_writelane_b32 v254, s3, 59
	s_lshl_b64 s[2:3], s[14:15], 20
	v_writelane_b32 v254, s2, 60
	v_fma_f32 v0, -v2, v1, v0
	s_ashr_i32 s1, s5, 30
	v_writelane_b32 v254, s3, 61
	s_mov_b32 s2, s12
	v_writelane_b32 v254, s2, 62
	s_or_b32 s1, s1, 1
	s_mov_b32 s11, 0xc2a00000
	v_writelane_b32 v254, s3, 63
	s_lshl_b64 s[2:3], s[12:13], 20
	v_writelane_b32 v255, s2, 0
	s_movk_i32 s13, 0x3c00
	s_mov_b32 s10, 0x3e38aa3b
	v_writelane_b32 v255, s3, 1
	s_mov_b32 s2, s6
	v_writelane_b32 v255, s2, 2
	s_mov_b32 s12, 0x3fb504f3
	v_readlane_b32 s43, v253, 25
	v_writelane_b32 v255, s3, 3
	s_lshl_b64 s[2:3], s[6:7], 20
	v_writelane_b32 v255, s2, 4
	v_readlane_b32 s44, v253, 26
	v_readlane_b32 s45, v253, 27
	v_writelane_b32 v255, s3, 5
	v_cmp_ge_f32_e64 s[2:3], |v0|, v1
	v_cvt_i32_f32_e32 v0, v2
	s_and_b64 s[2:3], s[2:3], exec
	v_writelane_b32 v255, s0, 6
	s_cselect_b32 s0, s1, 0
	v_readfirstlane_b32 s1, v0
	s_add_i32 s0, s1, s0
	s_mul_i32 s1, s0, s9
	s_sub_i32 s1, s5, s1
	s_sext_i32_i16 s1, s1
	s_add_i32 s2, s4, s1
	s_sext_i32_i16 s1, s0
	v_writelane_b32 v255, s1, 7
	s_bfe_i64 s[0:1], s[0:1], 0x100000
	s_lshl_b64 s[0:1], s[0:1], 20
	v_writelane_b32 v255, s0, 8
	s_ashr_i32 s3, s2, 31
	v_mbcnt_lo_u32_b32 v0, -1, 0
	v_writelane_b32 v255, s1, 9
	s_lshl_b32 s0, s96, 8
	v_writelane_b32 v255, s0, 10
	s_lshl_b32 s0, s86, 8
	v_writelane_b32 v255, s0, 11
	s_lshl_b32 s0, s96, 1
	v_writelane_b32 v255, s0, 12
	s_lshl_b32 s0, s86, 1
	v_writelane_b32 v255, s0, 13
	s_lshl_b32 s0, s96, 2
	v_writelane_b32 v255, s0, 14
	s_lshl_b32 s0, s86, 2
	v_writelane_b32 v255, s0, 15
	s_lshl_b32 s0, s96, 7
	v_writelane_b32 v255, s0, 16
	s_lshl_b32 s0, s86, 7
	v_writelane_b32 v255, s0, 17
	s_lshl_b32 s0, s96, 10
	v_writelane_b32 v255, s0, 18
	s_lshl_b32 s0, s86, 10
	v_writelane_b32 v255, s0, 19
	s_lshl_b32 s0, s96, 12
	v_writelane_b32 v255, s0, 20
	s_lshl_b32 s0, s86, 12
	v_writelane_b32 v255, s0, 21
	s_lshl_b32 s0, s96, 6
	v_writelane_b32 v255, s0, 22
	s_lshl_b32 s0, s86, 6
	v_writelane_b32 v255, s0, 23
	s_add_i32 s0, 0, 0x23fc0
	v_writelane_b32 v255, s0, 24
	s_add_i32 s0, 0, 0x23fc4
	v_writelane_b32 v255, s0, 25
	s_add_i32 s0, 0, 0x23fc8
	v_writelane_b32 v255, s0, 26
	s_add_i32 s0, 0, 0x23fcc
	v_writelane_b32 v255, s0, 27
	s_add_i32 s0, 0, 0x23fd0
	v_writelane_b32 v255, s0, 28
	s_add_i32 s0, 0, 0x9000
	v_writelane_b32 v255, s0, 29
	s_add_i32 s0, 0, 0x1bc00
	v_writelane_b32 v255, s0, 30
	s_add_i32 s0, 0, 0x14400
	v_writelane_b32 v255, s0, 31
	s_add_i32 s0, 0, 0x19400
	v_writelane_b32 v255, s0, 32
	s_mov_b32 s0, s2
	v_writelane_b32 v255, s0, 33
	v_mbcnt_hi_u32_b32 v223, -1, v0
	s_mov_b64 s[8:9], 0
	v_writelane_b32 v255, s1, 34
	s_lshl_b64 s[0:1], s[2:3], 20
	v_writelane_b32 v255, s0, 35
	s_mov_b32 s2, s29
	v_readlane_b32 s48, v253, 30
	v_writelane_b32 v255, s1, 36
	s_lshl_b64 s[0:1], s[96:97], 15
	v_writelane_b32 v255, s0, 37
	v_readlane_b32 s49, v253, 31
	v_readlane_b32 s50, v253, 32
	v_writelane_b32 v255, s1, 38
	s_lshl_b64 s[0:1], s[86:87], 15
	v_writelane_b32 v255, s0, 39
	v_readlane_b32 s51, v253, 33
	s_nop 0
	v_writelane_b32 v255, s1, 40
	s_mov_b64 s[0:1], -1
	v_writelane_b32 v255, s0, 41
	s_nop 1
	v_writelane_b32 v255, s1, 42
	v_writelane_b32 v255, s96, 43
	s_nop 1
	v_writelane_b32 v255, s97, 44
	s_branch .LBB0_253

; __device__ __forceinline__ unsigned xb_add(unsigned* p, unsigned v) { return __hip_atomic_fetch_add(p, v, __ATOMIC_RELAXED, __HIP_MEMORY_SCOPE_AGENT); }
; __device__ __forceinline__ void xcd_barrier(const XcdBarrier& b) {
;     asm volatile("s_waitcnt vmcnt(0)" ::: "memory");
;     __syncthreads();
;     if (threadIdx.x == 0) {
;         unsigned* bar = b.bar;
;         __builtin_amdgcn_s_waitcnt(0);
;         unsigned nloc = b.st[0], nx = b.st[1];
;         if (nloc == 0u) { xcd_barrier_complete(bar, b.x, nloc, nx); b.st[0] = nloc; b.st[1] = nx; }
;         const unsigned old = xb_add(&bar[XB_XSUB(b.x)], 1u);
.LBB0_344:
	v_readlane_b32 s0, v255, 47
	s_add_i32 s28, s0, 2
	s_cmp_ge_i32 s28, s23
	s_cbranch_scc1 .LBB0_515
	s_mov_b64 s[0:1], -1
	s_cmpk_eq_i32 s86, 0x100
	s_cbranch_scc1 .LBB0_399
	s_and_b64 vcc, exec, s[94:95]
	s_cbranch_vccz .LBB0_399
	s_waitcnt vmcnt(0)
	s_waitcnt vmcnt(0) lgkmcnt(0)
	s_barrier
	s_mov_b64 s[0:1], exec
	v_readlane_b32 s2, v253, 0
	v_readlane_b32 s3, v253, 1
	s_and_b64 s[2:3], s[0:1], s[2:3]
	s_mov_b64 exec, s[2:3]
	s_cbranch_execz .LBB0_398
	v_readlane_b32 s2, v255, 24
	s_waitcnt vmcnt(0) expcnt(0) lgkmcnt(0)
	s_nop 0
	v_mov_b32_e32 v0, s2
	ds_read_b32 v2, v0
	v_readlane_b32 s2, v255, 25
	s_waitcnt lgkmcnt(0)
	v_cmp_ne_u32_e32 vcc, 0, v2
	v_mov_b32_e32 v0, s2
	ds_read_b32 v0, v0
	s_cbranch_vccnz .LBB0_362
	s_mov_b32 s14, 1
	s_branch .LBB0_350

.LBB0_427:
	s_or_b64 exec, exec, s[0:1]
	v_mov_b32_e32 v0, v252
	v_readlane_b32 s3, v254, 33
	v_readfirstlane_b32 s0, v0
	s_ashr_i32 s2, s0, 6
	s_add_i32 s26, s3, s2
	s_movk_i32 s101, 0x217f
	s_cmpk_lg_i32 s86, 0x100
	s_cbranch_scc1 .Lseam1_init_done
	s_movk_i32 s26, 0x7000
	s_cmpk_lt_u32 s96, 0xc0
	s_cbranch_scc1 .Lseam1_init_done
	s_sub_i32 s3, s96, 0xc0
	s_lshl_b32 s3, s3, 3
	s_add_i32 s26, s3, s2
	v_readlane_b32 s3, v255, 45
	s_cmp_eq_u32 s3, 0
	s_cbranch_scc0 .Lseam1_l1
	s_addk_i32 s26, 0x1980
	s_branch .Lseam1_init_done
.Lseam1_l1:
	s_addk_i32 s26, 0x2680
	s_movk_i32 s101, 0x2a7f
.Lseam1_init_done:
	s_mov_b64 s[0:1], s[20:21]
	s_cmp_gt_i32 s26, s101
	s_cbranch_scc1 .LBB0_476
	s_add_u32 s27, s0, 0x200000
	s_addc_u32 s36, s1, 0
	s_add_u32 s37, s0, 0x3e00000
	s_addc_u32 s38, s1, 0
	s_add_u32 s39, s0, 0x4e00000
	s_addc_u32 s40, s1, 0
	s_add_u32 s41, s0, 0x5e00000
	s_addc_u32 s42, s1, 0
	s_add_u32 s43, s0, 0x10000
	s_addc_u32 s44, s1, 0
	v_and_b32_e32 v2, 63, v0
	v_bfe_u32 v69, v0, 4, 2
	v_bfe_u32 v80, v0, 3, 3
	v_lshlrev_b32_e32 v0, 3, v0
	s_add_u32 s45, s0, 0x14000
	s_mulk_i32 s2, 0x4100
	v_and_b32_e32 v70, 56, v0
	s_addc_u32 s46, s1, 0
	s_add_i32 s0, s2, 0
	v_lshlrev_b32_e32 v168, 2, v2
	v_mul_u32_u24_e32 v0, 0x104, v70
	v_lshlrev_b32_e32 v3, 2, v80
	v_and_b32_e32 v68, 60, v168
	v_add3_u32 v81, s0, v0, v3
	v_or_b32_e32 v0, 4, v69
	v_lshl_add_u32 v1, v68, 2, s0
	s_movk_i32 s1, 0x104
	v_mul_u32_u24_e32 v0, 0x104, v0
	v_mad_u32_u24 v71, v69, s1, v1
	v_or_b32_e32 v82, 8, v80
	v_or_b32_e32 v83, 16, v80
	v_or_b32_e32 v84, 24, v80
	v_or_b32_e32 v85, 32, v80
	v_or_b32_e32 v86, 40, v80
	v_or_b32_e32 v87, 48, v80
	v_or_b32_e32 v88, 56, v80
	v_add_u32_e32 v89, s0, v168
	v_lshl_add_u64 v[72:73], s[16:17], 0, v[168:169]
	v_lshlrev_b32_e32 v74, 2, v2
	v_add_u32_e32 v90, v1, v0
	s_branch .LBB0_430
.LBB0_429:
	v_readlane_b32 s0, v253, 34
	s_cmpk_eq_i32 s86, 0x100
	s_cselect_b32 s0, 0x200, s0
	s_add_i32 s26, s26, s0
	s_cmp_gt_i32 s26, s101
	s_cbranch_scc1 .LBB0_476
